# m1+m2+m6+m8: norm-gain vectors hoisted out of the fused-epilogue store loops (no per-iteration wait behind stores)
# baseline (speedup 1.0000x reference)
;     __device__ __forceinline__ void fused(pg8::f32x4 (&acc)[2][2][4][2], const pg8::Unit& u, int wr, int wc, int fr, int fq, LAS unsigned char* lds, int wid, int lane) const {
;     ...
;         for (int ai = 0; ai < 2; ++ai)
; #pragma unroll
;             for (int m = 0; m < 4; ++m) { const int r = ai * 128 + wr * 64 + m * 16 + fr; const float s3 = S[r]; const size_t off = (size_t)(b * TB + u.pm * 256 + r) * D + col0;
; #pragma unroll
;                 for (int bj = 0; bj < 2; ++bj) {
;                     const f32x4 b0 = pre[m][bj][0], b1 = pre[m][bj][1];
;                     const f32x4 h0 = *(const f32x4*)(g3 + col0 + bj * 128), h1 = *(const f32x4*)(g3 + col0 + bj * 128 + 4);
;                     const f32x4 x0 = b0 + acc[ai][bj][m][0] * s3 * h0, x1 = b1 + acc[ai][bj][m][1] * s3 * h1;
;                     *(f32x4*)(X + off + bj * 128) = x0; *(f32x4*)(X + off + bj * 128 + 4) = x1;
;                     st8bf(H2o + off + bj * 128, x0, x1); }
.LBB0_220:
	s_or_b64 exec, exec, s[14:15]
	s_lshl_b32 s0, s82, 10
	s_ashr_i32 s1, s0, 31
	s_lshl_b64 s[0:1], s[0:1], 2
	s_add_u32 s0, s8, s0
	s_addc_u32 s1, s9, s1
	s_waitcnt lgkmcnt(0)
	s_barrier
	v_lshl_add_u64 v[220:221], v[212:213], 2, s[0:1]
	global_load_dwordx4 v[232:235], v[220:221], off
	global_load_dwordx4 v[236:239], v[220:221], off offset:16
	global_load_dwordx4 v[240:243], v[220:221], off offset:512
	global_load_dwordx4 v[244:247], v[220:221], off offset:528
	v_lshl_add_u32 v192, v231, 2, 0
	v_add_u32_e32 v192, 0x2000, v192
	ds_read2_b32 v[196:197], v192 offset1:16
	v_lshlrev_b64 v[194:195], 10, v[216:217]
	s_add_u32 s6, s10, 0x13a00000
	v_lshl_add_u64 v[194:195], v[194:195], 0, v[212:213]
	s_addc_u32 s7, s11, 0
	s_waitcnt lgkmcnt(0)
	v_pk_mul_f32 v[126:127], v[126:127], v[196:197] op_sel_hi:[1,0]
	v_pk_mul_f32 v[124:125], v[124:125], v[196:197] op_sel_hi:[1,0]
	v_pk_mul_f32 v[202:203], v[122:123], v[196:197] op_sel_hi:[1,0]
	v_pk_mul_f32 v[204:205], v[120:121], v[196:197] op_sel_hi:[1,0]
	v_lshl_add_u64 v[194:195], v[194:195], 1, s[6:7]
	v_pk_mul_f32 v[118:119], v[118:119], v[196:197] op_sel_hi:[1,0]
	v_pk_mul_f32 v[116:117], v[116:117], v[196:197] op_sel_hi:[1,0]
	s_waitcnt vmcnt(3)
	v_pk_fma_f32 v[120:121], v[232:233], v[124:125], v[188:189]
	v_pk_fma_f32 v[122:123], v[234:235], v[126:127], v[190:191]
	s_waitcnt vmcnt(2)
	v_pk_fma_f32 v[124:125], v[236:237], v[204:205], v[184:185]
	v_pk_fma_f32 v[126:127], v[238:239], v[202:203], v[186:187]
	global_store_dwordx4 v[218:219], v[120:123], off
	global_store_dwordx4 v[218:219], v[124:127], off offset:16
	v_pk_mul_f32 v[184:185], v[114:115], v[196:197] op_sel_hi:[1,0]
	v_cvt_pk_bf16_f32 v120, v120, v121
	v_cvt_pk_bf16_f32 v121, v122, v123
	v_cvt_pk_bf16_f32 v122, v124, v125
	v_cvt_pk_bf16_f32 v123, v126, v127
	global_store_dwordx4 v[194:195], v[120:123], off
	s_nop 0
	v_pk_mul_f32 v[186:187], v[112:113], v[196:197] op_sel_hi:[1,0]
	s_waitcnt vmcnt(4)
	v_pk_fma_f32 v[112:113], v[116:117], v[240:241], v[180:181]
	v_pk_fma_f32 v[114:115], v[118:119], v[242:243], v[182:183]
	s_waitcnt vmcnt(3)
	v_pk_fma_f32 v[116:117], v[186:187], v[244:245], v[176:177]
	v_pk_fma_f32 v[118:119], v[184:185], v[246:247], v[178:179]
	global_store_dwordx4 v[218:219], v[112:115], off offset:512
	global_store_dwordx4 v[218:219], v[116:119], off offset:528
	v_add_u32_e32 v120, 16, v216
	v_cvt_pk_bf16_f32 v112, v112, v113
	v_cvt_pk_bf16_f32 v113, v114, v115
	v_cvt_pk_bf16_f32 v114, v116, v117
	v_cvt_pk_bf16_f32 v115, v118, v119
	global_store_dwordx4 v[194:195], v[112:115], off offset:256
	s_nop 0
	v_ashrrev_i32_e32 v121, 31, v120
	v_mov_b32_e32 v124, v197
	v_lshlrev_b64 v[122:123], 10, v[120:121]
	v_lshlrev_b64 v[120:121], 12, v[120:121]
	v_pk_mul_f32 v[110:111], v[110:111], v[124:125] op_sel_hi:[1,0]
	v_pk_mul_f32 v[108:109], v[108:109], v[124:125] op_sel_hi:[1,0]
	v_pk_mul_f32 v[126:127], v[106:107], v[124:125] op_sel_hi:[1,0]
	v_pk_mul_f32 v[176:177], v[104:105], v[124:125] op_sel_hi:[1,0]
	v_lshl_add_u64 v[122:123], v[122:123], 0, v[212:213]
	v_lshl_add_u64 v[120:121], v[214:215], 0, v[120:121]
	v_lshl_add_u64 v[122:123], v[122:123], 1, s[6:7]
	v_pk_mul_f32 v[102:103], v[102:103], v[124:125] op_sel_hi:[1,0]
	v_pk_mul_f32 v[100:101], v[100:101], v[124:125] op_sel_hi:[1,0]
	v_pk_fma_f32 v[104:105], v[232:233], v[108:109], v[172:173]
	v_pk_fma_f32 v[106:107], v[234:235], v[110:111], v[174:175]
	v_pk_fma_f32 v[108:109], v[236:237], v[176:177], v[168:169]
	v_pk_fma_f32 v[110:111], v[238:239], v[126:127], v[170:171]
	global_store_dwordx4 v[120:121], v[104:107], off
	global_store_dwordx4 v[120:121], v[108:111], off offset:16
	v_pk_mul_f32 v[112:113], v[98:99], v[124:125] op_sel_hi:[1,0]
	v_cvt_pk_bf16_f32 v104, v104, v105
	v_cvt_pk_bf16_f32 v105, v106, v107
	v_cvt_pk_bf16_f32 v106, v108, v109
	v_cvt_pk_bf16_f32 v107, v110, v111
	global_store_dwordx4 v[122:123], v[104:107], off
	s_nop 0
	v_pk_mul_f32 v[114:115], v[96:97], v[124:125] op_sel_hi:[1,0]
	v_pk_fma_f32 v[96:97], v[100:101], v[240:241], v[164:165]
	v_pk_fma_f32 v[98:99], v[102:103], v[242:243], v[166:167]
	v_pk_fma_f32 v[100:101], v[114:115], v[244:245], v[160:161]
	v_pk_fma_f32 v[102:103], v[112:113], v[246:247], v[162:163]
	global_store_dwordx4 v[120:121], v[96:99], off offset:512
	global_store_dwordx4 v[120:121], v[100:103], off offset:528
	v_add_u32_e32 v104, 32, v216
	v_cvt_pk_bf16_f32 v96, v96, v97
	v_cvt_pk_bf16_f32 v97, v98, v99
	v_cvt_pk_bf16_f32 v98, v100, v101
	v_cvt_pk_bf16_f32 v99, v102, v103
	global_store_dwordx4 v[122:123], v[96:99], off offset:256
	s_nop 0
	ds_read2_b32 v[106:107], v192 offset0:32 offset1:48
	v_ashrrev_i32_e32 v105, 31, v104
	v_lshlrev_b64 v[108:109], 10, v[104:105]
	v_lshlrev_b64 v[104:105], 12, v[104:105]
	v_lshl_add_u64 v[108:109], v[108:109], 0, v[212:213]
	s_waitcnt lgkmcnt(0)
;     __device__ __forceinline__ void fused(pg8::f32x4 (&acc)[2][2][4][2], const pg8::Unit& u, int wr, int wc, int fr, int fq, LAS unsigned char* lds, int wid, int lane) const {
;     ...
;             for (int m = 0; m < 4; ++m) { const int r = ai * 128 + wr * 64 + m * 16 + fr; const float s3 = S[r]; const size_t off = (size_t)(b * TB + u.pm * 256 + r) * D + col0;
; #pragma unroll
;                 for (int bj = 0; bj < 2; ++bj) {
;                     const f32x4 b0 = pre[m][bj][0], b1 = pre[m][bj][1];
;                     const f32x4 h0 = *(const f32x4*)(g3 + col0 + bj * 128), h1 = *(const f32x4*)(g3 + col0 + bj * 128 + 4);
;                     const f32x4 x0 = b0 + acc[ai][bj][m][0] * s3 * h0, x1 = b1 + acc[ai][bj][m][1] * s3 * h1;
;                     *(f32x4*)(X + off + bj * 128) = x0; *(f32x4*)(X + off + bj * 128 + 4) = x1;
;                     st8bf(H2o + off + bj * 128, x0, x1); }
;                 if (ai == 0 && m == 3) {
;                     asm volatile("" ::: "memory");
; #pragma unroll
;                     for (int m2 = 0; m2 < 4; ++m2) { const size_t off2 = (size_t)(b * TB + u.pm * 256 + 128 + wr * 64 + m2 * 16 + fr) * D + col0;
; #pragma unroll
;                         for (int bj = 0; bj < 2; ++bj)
; #pragma unroll
;                             for (int n = 0; n < 2; ++n) pre[m2][bj][n] = *(const f32x4*)(X + off2 + bj * 128 + n * 4); }
;                 } }
	v_pk_mul_f32 v[92:93], v[92:93], v[106:107] op_sel_hi:[1,0]
	v_pk_mul_f32 v[94:95], v[94:95], v[106:107] op_sel_hi:[1,0]
	v_pk_mul_f32 v[110:111], v[88:89], v[106:107] op_sel_hi:[1,0]
	v_pk_mul_f32 v[112:113], v[90:91], v[106:107] op_sel_hi:[1,0]
	v_lshl_add_u64 v[104:105], v[214:215], 0, v[104:105]
	v_lshl_add_u64 v[108:109], v[108:109], 1, s[6:7]
	v_pk_mul_f32 v[86:87], v[86:87], v[106:107] op_sel_hi:[1,0]
	v_pk_mul_f32 v[84:85], v[84:85], v[106:107] op_sel_hi:[1,0]
	v_pk_fma_f32 v[90:91], v[234:235], v[94:95], v[158:159]
	v_pk_fma_f32 v[88:89], v[232:233], v[92:93], v[156:157]
	v_pk_fma_f32 v[94:95], v[238:239], v[112:113], v[154:155]
	v_pk_fma_f32 v[92:93], v[236:237], v[110:111], v[152:153]
	global_store_dwordx4 v[104:105], v[88:91], off
	global_store_dwordx4 v[104:105], v[92:95], off offset:16
	v_pk_mul_f32 v[96:97], v[82:83], v[106:107] op_sel_hi:[1,0]
	v_cvt_pk_bf16_f32 v88, v88, v89
	v_cvt_pk_bf16_f32 v89, v90, v91
	v_cvt_pk_bf16_f32 v90, v92, v93
	v_cvt_pk_bf16_f32 v91, v94, v95
	global_store_dwordx4 v[108:109], v[88:91], off
	s_nop 0
	v_pk_mul_f32 v[98:99], v[80:81], v[106:107] op_sel_hi:[1,0]
	v_pk_fma_f32 v[80:81], v[84:85], v[240:241], v[148:149]
	v_pk_fma_f32 v[82:83], v[86:87], v[242:243], v[150:151]
	v_pk_fma_f32 v[84:85], v[98:99], v[244:245], v[144:145]
	v_pk_fma_f32 v[86:87], v[96:97], v[246:247], v[146:147]
	global_store_dwordx4 v[104:105], v[80:83], off offset:512
	global_store_dwordx4 v[104:105], v[84:87], off offset:528
	v_add_u32_e32 v88, 48, v216
	v_cvt_pk_bf16_f32 v80, v80, v81
	v_cvt_pk_bf16_f32 v81, v82, v83
	v_cvt_pk_bf16_f32 v82, v84, v85
	v_cvt_pk_bf16_f32 v83, v86, v87
	global_store_dwordx4 v[108:109], v[80:83], off offset:256
	s_nop 0
	v_ashrrev_i32_e32 v89, 31, v88
	v_mov_b32_e32 v92, v107
	v_lshlrev_b64 v[90:91], 10, v[88:89]
	v_lshlrev_b64 v[88:89], 12, v[88:89]
	v_pk_mul_f32 v[76:77], v[76:77], v[92:93] op_sel_hi:[1,0]
	v_pk_mul_f32 v[78:79], v[78:79], v[92:93] op_sel_hi:[1,0]
	v_pk_mul_f32 v[94:95], v[72:73], v[92:93] op_sel_hi:[1,0]
	v_pk_mul_f32 v[96:97], v[74:75], v[92:93] op_sel_hi:[1,0]
	v_lshl_add_u64 v[90:91], v[90:91], 0, v[212:213]
	v_lshl_add_u64 v[88:89], v[214:215], 0, v[88:89]
	v_lshl_add_u64 v[90:91], v[90:91], 1, s[6:7]
	v_pk_mul_f32 v[70:71], v[70:71], v[92:93] op_sel_hi:[1,0]
	v_pk_mul_f32 v[68:69], v[68:69], v[92:93] op_sel_hi:[1,0]
	v_add_u32_e32 v144, 0x90, v216
	v_add_u32_e32 v146, 0xa0, v216
	v_ashrrev_i32_e32 v145, 31, v144
	v_ashrrev_i32_e32 v147, 31, v146
	v_pk_fma_f32 v[74:75], v[234:235], v[78:79], v[142:143]
	v_pk_fma_f32 v[72:73], v[232:233], v[76:77], v[140:141]
	v_pk_fma_f32 v[78:79], v[238:239], v[96:97], v[138:139]
	v_pk_fma_f32 v[76:77], v[236:237], v[94:95], v[136:137]
	global_store_dwordx4 v[88:89], v[72:75], off
	global_store_dwordx4 v[88:89], v[76:79], off offset:16
	v_add_u32_e32 v80, 0x80, v216
	v_cvt_pk_bf16_f32 v72, v72, v73
	v_cvt_pk_bf16_f32 v73, v74, v75
	v_cvt_pk_bf16_f32 v74, v76, v77
	v_cvt_pk_bf16_f32 v75, v78, v79
	global_store_dwordx4 v[90:91], v[72:75], off
	s_nop 0
	v_ashrrev_i32_e32 v81, 31, v80
	v_lshlrev_b64 v[82:83], 12, v[80:81]
	v_lshl_add_u64 v[142:143], v[214:215], 0, v[82:83]
	v_pk_mul_f32 v[82:83], v[66:67], v[92:93] op_sel_hi:[1,0]
	v_pk_mul_f32 v[84:85], v[64:65], v[92:93] op_sel_hi:[1,0]
	v_pk_fma_f32 v[64:65], v[68:69], v[240:241], v[132:133]
	v_pk_fma_f32 v[66:67], v[70:71], v[242:243], v[134:135]
	v_pk_fma_f32 v[68:69], v[84:85], v[244:245], v[128:129]
	v_pk_fma_f32 v[70:71], v[82:83], v[246:247], v[130:131]
	global_store_dwordx4 v[88:89], v[64:67], off offset:512
	global_store_dwordx4 v[88:89], v[68:71], off offset:528
	s_nop 0
	v_cvt_pk_bf16_f32 v64, v64, v65
	v_cvt_pk_bf16_f32 v65, v66, v67
	v_cvt_pk_bf16_f32 v66, v68, v69
	v_cvt_pk_bf16_f32 v67, v70, v71
	global_store_dwordx4 v[90:91], v[64:67], off offset:256
	global_load_dwordx4 v[98:101], v[142:143], off
	global_load_dwordx4 v[102:105], v[142:143], off offset:16
	v_add_u32_e32 v90, 0xb0, v216
	v_ashrrev_i32_e32 v91, 31, v90
	v_lshlrev_b64 v[64:65], 12, v[144:145]
	v_lshlrev_b64 v[66:67], 12, v[146:147]
	v_lshlrev_b64 v[68:69], 12, v[90:91]
	v_lshl_add_u64 v[148:149], v[214:215], 0, v[64:65]
	v_lshlrev_b64 v[70:71], 10, v[80:81]
	v_lshl_add_u64 v[92:93], v[214:215], 0, v[66:67]
	v_lshl_add_u64 v[88:89], v[214:215], 0, v[68:69]
	global_load_dwordx4 v[110:113], v[148:149], off offset:16
	global_load_dwordx4 v[114:117], v[148:149], off
	global_load_dwordx4 v[118:121], v[148:149], off offset:528
	global_load_dwordx4 v[122:125], v[148:149], off offset:512
	global_load_dwordx4 v[126:129], v[92:93], off offset:16
	global_load_dwordx4 v[130:133], v[92:93], off
	global_load_dwordx4 v[80:83], v[92:93], off offset:528
	global_load_dwordx4 v[84:87], v[92:93], off offset:512
	global_load_dwordx4 v[72:75], v[88:89], off offset:16
	global_load_dwordx4 v[76:79], v[88:89], off
	ds_read2_b32 v[152:153], v192 offset0:128 offset1:144
	v_lshl_add_u64 v[64:65], v[70:71], 0, v[212:213]
	v_lshl_add_u64 v[150:151], v[64:65], 1, s[6:7]
	global_load_dwordx4 v[64:67], v[88:89], off offset:528
	global_load_dwordx4 v[68:71], v[88:89], off offset:512
	global_load_dwordx4 v[134:137], v[142:143], off offset:528
	global_load_dwordx4 v[138:141], v[142:143], off offset:512
	s_waitcnt lgkmcnt(0)
	v_pk_mul_f32 v[60:61], v[60:61], v[152:153] op_sel_hi:[1,0]
	v_pk_mul_f32 v[62:63], v[62:63], v[152:153] op_sel_hi:[1,0]
	v_pk_mul_f32 v[154:155], v[56:57], v[152:153] op_sel_hi:[1,0]
	v_pk_mul_f32 v[156:157], v[58:59], v[152:153] op_sel_hi:[1,0]
	v_pk_mul_f32 v[54:55], v[54:55], v[152:153] op_sel_hi:[1,0]
	v_pk_mul_f32 v[52:53], v[52:53], v[152:153] op_sel_hi:[1,0]
	s_waitcnt vmcnt(15)
;     __device__ __forceinline__ void fused(pg8::f32x4 (&acc)[2][2][4][2], const pg8::Unit& u, int wr, int wc, int fr, int fq, LAS unsigned char* lds, int wid, int lane) const {
;     ...
;             for (int m = 0; m < 4; ++m) { const int r = ai * 128 + wr * 64 + m * 16 + fr; const float s3 = S[r]; const size_t off = (size_t)(b * TB + u.pm * 256 + r) * D + col0;
; #pragma unroll
;                 for (int bj = 0; bj < 2; ++bj) {
;                     const f32x4 b0 = pre[m][bj][0], b1 = pre[m][bj][1];
;                     const f32x4 h0 = *(const f32x4*)(g3 + col0 + bj * 128), h1 = *(const f32x4*)(g3 + col0 + bj * 128 + 4);
;                     const f32x4 x0 = b0 + acc[ai][bj][m][0] * s3 * h0, x1 = b1 + acc[ai][bj][m][1] * s3 * h1;
;                     *(f32x4*)(X + off + bj * 128) = x0; *(f32x4*)(X + off + bj * 128 + 4) = x1;
;                     st8bf(H2o + off + bj * 128, x0, x1); }
	v_pk_fma_f32 v[58:59], v[234:235], v[62:63], v[100:101]
	v_pk_fma_f32 v[56:57], v[232:233], v[60:61], v[98:99]
	s_waitcnt vmcnt(14)
	v_pk_fma_f32 v[62:63], v[238:239], v[156:157], v[104:105]
	v_pk_fma_f32 v[60:61], v[236:237], v[154:155], v[102:103]
	global_store_dwordx4 v[142:143], v[56:59], off
	global_store_dwordx4 v[142:143], v[60:63], off offset:16
	v_pk_mul_f32 v[94:95], v[50:51], v[152:153] op_sel_hi:[1,0]
	v_cvt_pk_bf16_f32 v56, v56, v57
	v_cvt_pk_bf16_f32 v57, v58, v59
	v_cvt_pk_bf16_f32 v58, v60, v61
	v_cvt_pk_bf16_f32 v59, v62, v63
	global_store_dwordx4 v[150:151], v[56:59], off
	s_nop 0
	v_pk_mul_f32 v[96:97], v[48:49], v[152:153] op_sel_hi:[1,0]
	s_waitcnt vmcnt(3)
	v_pk_fma_f32 v[48:49], v[52:53], v[240:241], v[138:139]
	v_pk_fma_f32 v[50:51], v[54:55], v[242:243], v[140:141]
	v_pk_fma_f32 v[52:53], v[96:97], v[244:245], v[134:135]
	v_pk_fma_f32 v[54:55], v[94:95], v[246:247], v[136:137]
	global_store_dwordx4 v[142:143], v[48:51], off offset:512
	global_store_dwordx4 v[142:143], v[52:55], off offset:528
	v_mov_b32_e32 v58, v153
	v_cvt_pk_bf16_f32 v48, v48, v49
	v_cvt_pk_bf16_f32 v49, v50, v51
	v_cvt_pk_bf16_f32 v50, v52, v53
	v_cvt_pk_bf16_f32 v51, v54, v55
	global_store_dwordx4 v[150:151], v[48:51], off offset:256
	s_nop 0
	v_lshlrev_b64 v[56:57], 10, v[144:145]
	v_pk_mul_f32 v[44:45], v[44:45], v[58:59] op_sel_hi:[1,0]
	v_pk_mul_f32 v[46:47], v[46:47], v[58:59] op_sel_hi:[1,0]
	v_pk_mul_f32 v[60:61], v[40:41], v[58:59] op_sel_hi:[1,0]
	v_pk_mul_f32 v[62:63], v[42:43], v[58:59] op_sel_hi:[1,0]
	v_lshl_add_u64 v[56:57], v[56:57], 0, v[212:213]
	v_lshl_add_u64 v[56:57], v[56:57], 1, s[6:7]
	v_pk_mul_f32 v[38:39], v[38:39], v[58:59] op_sel_hi:[1,0]
	v_pk_mul_f32 v[36:37], v[36:37], v[58:59] op_sel_hi:[1,0]
	v_pk_fma_f32 v[42:43], v[234:235], v[46:47], v[116:117]
	v_pk_fma_f32 v[40:41], v[232:233], v[44:45], v[114:115]
	v_pk_fma_f32 v[46:47], v[238:239], v[62:63], v[112:113]
	v_pk_fma_f32 v[44:45], v[236:237], v[60:61], v[110:111]
	global_store_dwordx4 v[148:149], v[40:43], off
	global_store_dwordx4 v[148:149], v[44:47], off offset:16
	v_pk_mul_f32 v[48:49], v[34:35], v[58:59] op_sel_hi:[1,0]
	v_cvt_pk_bf16_f32 v40, v40, v41
	v_cvt_pk_bf16_f32 v41, v42, v43
	v_cvt_pk_bf16_f32 v42, v44, v45
	v_cvt_pk_bf16_f32 v43, v46, v47
	global_store_dwordx4 v[56:57], v[40:43], off
	s_nop 0
	v_pk_mul_f32 v[50:51], v[32:33], v[58:59] op_sel_hi:[1,0]
	v_pk_fma_f32 v[32:33], v[36:37], v[240:241], v[122:123]
	v_pk_fma_f32 v[34:35], v[38:39], v[242:243], v[124:125]
	v_pk_fma_f32 v[36:37], v[50:51], v[244:245], v[118:119]
	v_pk_fma_f32 v[38:39], v[48:49], v[246:247], v[120:121]
	global_store_dwordx4 v[148:149], v[32:35], off offset:512
	global_store_dwordx4 v[148:149], v[36:39], off offset:528
	v_lshlrev_b64 v[42:43], 10, v[146:147]
	v_cvt_pk_bf16_f32 v32, v32, v33
	v_cvt_pk_bf16_f32 v33, v34, v35
	v_cvt_pk_bf16_f32 v34, v36, v37
	v_cvt_pk_bf16_f32 v35, v38, v39
	global_store_dwordx4 v[56:57], v[32:35], off offset:256
	s_nop 0
	ds_read2_b32 v[40:41], v192 offset0:160 offset1:176
	v_lshl_add_u64 v[42:43], v[42:43], 0, v[212:213]
	v_lshl_add_u64 v[42:43], v[42:43], 1, s[6:7]
	s_waitcnt lgkmcnt(0)
	v_pk_mul_f32 v[28:29], v[28:29], v[40:41] op_sel_hi:[1,0]
	v_pk_mul_f32 v[30:31], v[30:31], v[40:41] op_sel_hi:[1,0]
	v_pk_mul_f32 v[44:45], v[24:25], v[40:41] op_sel_hi:[1,0]
	v_pk_mul_f32 v[46:47], v[26:27], v[40:41] op_sel_hi:[1,0]
	v_pk_mul_f32 v[22:23], v[22:23], v[40:41] op_sel_hi:[1,0]
	v_pk_mul_f32 v[20:21], v[20:21], v[40:41] op_sel_hi:[1,0]
	v_pk_fma_f32 v[26:27], v[234:235], v[30:31], v[132:133]
	v_pk_fma_f32 v[24:25], v[232:233], v[28:29], v[130:131]
	v_pk_fma_f32 v[30:31], v[238:239], v[46:47], v[128:129]
	v_pk_fma_f32 v[28:29], v[236:237], v[44:45], v[126:127]
	global_store_dwordx4 v[92:93], v[24:27], off
	global_store_dwordx4 v[92:93], v[28:31], off offset:16
	v_pk_mul_f32 v[32:33], v[18:19], v[40:41] op_sel_hi:[1,0]
	v_cvt_pk_bf16_f32 v24, v24, v25
	v_cvt_pk_bf16_f32 v25, v26, v27
	v_cvt_pk_bf16_f32 v26, v28, v29
	v_cvt_pk_bf16_f32 v27, v30, v31
	global_store_dwordx4 v[42:43], v[24:27], off
	s_nop 0
	v_pk_mul_f32 v[34:35], v[16:17], v[40:41] op_sel_hi:[1,0]
	v_pk_fma_f32 v[16:17], v[20:21], v[240:241], v[84:85]
	v_pk_fma_f32 v[18:19], v[22:23], v[242:243], v[86:87]
	v_pk_fma_f32 v[20:21], v[34:35], v[244:245], v[80:81]
	v_pk_fma_f32 v[22:23], v[32:33], v[246:247], v[82:83]
	global_store_dwordx4 v[92:93], v[16:19], off offset:512
	global_store_dwordx4 v[92:93], v[20:23], off offset:528
	v_mov_b32_e32 v26, v41
	v_cvt_pk_bf16_f32 v16, v16, v17
	v_cvt_pk_bf16_f32 v17, v18, v19
	v_cvt_pk_bf16_f32 v18, v20, v21
	v_cvt_pk_bf16_f32 v19, v22, v23
	global_store_dwordx4 v[42:43], v[16:19], off offset:256
	s_nop 0
	v_lshlrev_b64 v[24:25], 10, v[90:91]
	v_pk_mul_f32 v[12:13], v[12:13], v[26:27] op_sel_hi:[1,0]
	v_pk_mul_f32 v[14:15], v[14:15], v[26:27] op_sel_hi:[1,0]
	v_pk_mul_f32 v[28:29], v[8:9], v[26:27] op_sel_hi:[1,0]
	v_pk_mul_f32 v[30:31], v[10:11], v[26:27] op_sel_hi:[1,0]
	v_lshl_add_u64 v[24:25], v[24:25], 0, v[212:213]
	v_lshl_add_u64 v[24:25], v[24:25], 1, s[6:7]
	v_pk_mul_f32 v[6:7], v[6:7], v[26:27] op_sel_hi:[1,0]
	v_pk_mul_f32 v[4:5], v[4:5], v[26:27] op_sel_hi:[1,0]
	v_pk_fma_f32 v[10:11], v[234:235], v[14:15], v[78:79]
	v_pk_fma_f32 v[8:9], v[232:233], v[12:13], v[76:77]
	v_pk_fma_f32 v[14:15], v[238:239], v[30:31], v[74:75]
	v_pk_fma_f32 v[12:13], v[236:237], v[28:29], v[72:73]
	global_store_dwordx4 v[88:89], v[8:11], off
	global_store_dwordx4 v[88:89], v[12:15], off offset:16
	v_pk_mul_f32 v[16:17], v[2:3], v[26:27] op_sel_hi:[1,0]
	v_cvt_pk_bf16_f32 v8, v8, v9
	v_cvt_pk_bf16_f32 v9, v10, v11
	v_cvt_pk_bf16_f32 v10, v12, v13
	v_cvt_pk_bf16_f32 v11, v14, v15
	global_store_dwordx4 v[24:25], v[8:11], off
	s_nop 0
	v_pk_mul_f32 v[18:19], v[0:1], v[26:27] op_sel_hi:[1,0]
	v_pk_fma_f32 v[0:1], v[4:5], v[240:241], v[68:69]
	v_pk_fma_f32 v[2:3], v[6:7], v[242:243], v[70:71]
	v_pk_fma_f32 v[4:5], v[18:19], v[244:245], v[64:65]
	v_pk_fma_f32 v[6:7], v[16:17], v[246:247], v[66:67]
	global_store_dwordx4 v[88:89], v[0:3], off offset:512
	global_store_dwordx4 v[88:89], v[4:7], off offset:528
	s_nop 0
	v_cvt_pk_bf16_f32 v0, v0, v1
	v_cvt_pk_bf16_f32 v1, v2, v3
	v_cvt_pk_bf16_f32 v2, v4, v5
	v_cvt_pk_bf16_f32 v3, v6, v7
	global_store_dwordx4 v[24:25], v[0:3], off offset:256
	s_cbranch_execz .LBB0_134
	s_branch .LBB0_150

;     __device__ __forceinline__ void fused(pg8::f32x4 (&acc)[2][2][4][2], const pg8::Unit& u, int wr, int wc, int fr, int fq, LAS unsigned char* lds, int wid, int lane) const {
;     ...
;         for (int ai = 0; ai < 2; ++ai)
; #pragma unroll
;             for (int m = 0; m < 4; ++m) { const int r = ai * 128 + wr * 64 + m * 16 + fr; const float s2 = S[r]; const size_t off = (size_t)(b * TB + u.pm * 256 + r) * D + col0;
; #pragma unroll
;                 for (int bj = 0; bj < 2; ++bj) { const f32x4 x0 = acc[ai][bj][m][0], x1 = acc[ai][bj][m][1];
;                     *(f32x4*)(xout + off + bj * 128) = x0; *(f32x4*)(xout + off + bj * 128 + 4) = x1;
;                     const f32x4 h0 = *(const f32x4*)(g2 + col0 + bj * 128), h1 = *(const f32x4*)(g2 + col0 + bj * 128 + 4);
;                     st8bf(H2o + off + bj * 128, x0 * s2 * h0, x1 * s2 * h1); }
;                 asm volatile("" ::: "memory"); }
.LBB0_304:
	s_or_b64 exec, exec, s[10:11]
	s_add_u32 s6, s14, 0x4a00000
	s_addc_u32 s7, s15, 0
	v_lshlrev_b64 v[130:131], 10, v[214:215]
	s_add_u32 s0, s18, s58
	v_lshl_add_u64 v[140:141], v[130:131], 0, v[212:213]
	s_addc_u32 s1, s19, s59
	v_lshl_add_u64 v[142:143], v[140:141], 2, s[12:13]
	s_waitcnt lgkmcnt(0)
	s_barrier
	s_waitcnt lgkmcnt(0)
	v_lshl_add_u64 v[128:129], v[212:213], 2, s[0:1]
	global_load_dwordx4 v[146:149], v[128:129], off
	global_load_dwordx4 v[150:153], v[128:129], off offset:16
	global_load_dwordx4 v[154:157], v[128:129], off offset:512
	global_load_dwordx4 v[158:161], v[128:129], off offset:528
	global_store_dwordx4 v[142:143], v[76:79], off
	global_store_dwordx4 v[142:143], v[72:75], off offset:16
	v_lshl_add_u32 v130, v231, 2, 0
	ds_read_b32 v144, v130 offset:8192
	v_lshl_add_u64 v[140:141], v[140:141], 1, s[6:7]
	s_waitcnt lgkmcnt(0)
	v_pk_mul_f32 v[76:77], v[76:77], v[144:145] op_sel_hi:[1,0]
	v_pk_mul_f32 v[78:79], v[78:79], v[144:145] op_sel_hi:[1,0]
	v_pk_mul_f32 v[72:73], v[72:73], v[144:145] op_sel_hi:[1,0]
	v_pk_mul_f32 v[74:75], v[74:75], v[144:145] op_sel_hi:[1,0]
	s_waitcnt vmcnt(5)
	v_pk_mul_f32 v[78:79], v[78:79], v[148:149]
	v_pk_mul_f32 v[76:77], v[76:77], v[146:147]
	s_waitcnt vmcnt(4)
	v_pk_mul_f32 v[132:133], v[74:75], v[152:153]
	v_pk_mul_f32 v[74:75], v[72:73], v[150:151]
	v_cvt_pk_bf16_f32 v72, v76, v77
	v_cvt_pk_bf16_f32 v73, v78, v79
	v_cvt_pk_bf16_f32 v74, v74, v75
	v_cvt_pk_bf16_f32 v75, v132, v133
	global_store_dwordx4 v[140:141], v[72:75], off
	global_store_dwordx4 v[142:143], v[80:83], off offset:512
	global_store_dwordx4 v[142:143], v[88:91], off offset:528
	s_nop 0
	v_add_u32_e32 v132, 16, v214
	v_ashrrev_i32_e32 v133, 31, v132
	v_pk_mul_f32 v[80:81], v[80:81], v[144:145] op_sel_hi:[1,0]
	v_pk_mul_f32 v[82:83], v[82:83], v[144:145] op_sel_hi:[1,0]
	v_pk_mul_f32 v[88:89], v[88:89], v[144:145] op_sel_hi:[1,0]
	v_pk_mul_f32 v[90:91], v[90:91], v[144:145] op_sel_hi:[1,0]
	v_lshlrev_b64 v[132:133], 10, v[132:133]
	v_lshl_add_u64 v[132:133], v[132:133], 0, v[212:213]
	v_lshl_add_u64 v[134:135], v[132:133], 2, s[12:13]
	s_waitcnt vmcnt(6)
	v_pk_mul_f32 v[74:75], v[82:83], v[156:157]
	v_pk_mul_f32 v[72:73], v[80:81], v[154:155]
	s_waitcnt vmcnt(5)
	v_pk_mul_f32 v[78:79], v[90:91], v[160:161]
	v_pk_mul_f32 v[76:77], v[88:89], v[158:159]
	v_cvt_pk_bf16_f32 v72, v72, v73
	v_cvt_pk_bf16_f32 v73, v74, v75
	v_cvt_pk_bf16_f32 v74, v76, v77
	v_cvt_pk_bf16_f32 v75, v78, v79
	global_store_dwordx4 v[140:141], v[72:75], off offset:256
	global_store_dwordx4 v[134:135], v[100:103], off
	global_store_dwordx4 v[134:135], v[96:99], off offset:16
	ds_read_b32 v80, v130 offset:8256
	v_lshl_add_u64 v[82:83], v[132:133], 1, s[6:7]
	s_waitcnt lgkmcnt(0)
	v_pk_mul_f32 v[88:89], v[100:101], v[80:81] op_sel_hi:[1,0]
	v_pk_mul_f32 v[90:91], v[102:103], v[80:81] op_sel_hi:[1,0]
	v_pk_mul_f32 v[96:97], v[96:97], v[80:81] op_sel_hi:[1,0]
	v_pk_mul_f32 v[98:99], v[98:99], v[80:81] op_sel_hi:[1,0]
	v_pk_mul_f32 v[100:101], v[116:117], v[80:81] op_sel_hi:[1,0]
	v_pk_mul_f32 v[74:75], v[90:91], v[148:149]
	v_pk_mul_f32 v[72:73], v[88:89], v[146:147]
	v_pk_mul_f32 v[78:79], v[98:99], v[152:153]
	v_pk_mul_f32 v[76:77], v[96:97], v[150:151]
	v_cvt_pk_bf16_f32 v72, v72, v73
	v_cvt_pk_bf16_f32 v73, v74, v75
	v_cvt_pk_bf16_f32 v74, v76, v77
	v_cvt_pk_bf16_f32 v75, v78, v79
	global_store_dwordx4 v[82:83], v[72:75], off
	global_store_dwordx4 v[134:135], v[108:111], off offset:512
	global_store_dwordx4 v[134:135], v[116:119], off offset:528
	s_nop 0
	v_add_u32_e32 v88, 32, v214
	v_ashrrev_i32_e32 v89, 31, v88
	v_pk_mul_f32 v[96:97], v[108:109], v[80:81] op_sel_hi:[1,0]
	v_pk_mul_f32 v[98:99], v[110:111], v[80:81] op_sel_hi:[1,0]
	v_pk_mul_f32 v[80:81], v[118:119], v[80:81] op_sel_hi:[1,0]
	v_lshlrev_b64 v[88:89], 10, v[88:89]
	v_lshl_add_u64 v[88:89], v[88:89], 0, v[212:213]
	v_lshl_add_u64 v[90:91], v[88:89], 2, s[12:13]
	v_pk_mul_f32 v[74:75], v[98:99], v[156:157]
	v_pk_mul_f32 v[72:73], v[96:97], v[154:155]
	v_pk_mul_f32 v[78:79], v[80:81], v[160:161]
	v_pk_mul_f32 v[76:77], v[100:101], v[158:159]
	v_cvt_pk_bf16_f32 v72, v72, v73
	v_cvt_pk_bf16_f32 v73, v74, v75
	v_cvt_pk_bf16_f32 v74, v76, v77
	v_cvt_pk_bf16_f32 v75, v78, v79
	global_store_dwordx4 v[82:83], v[72:75], off offset:256
	global_store_dwordx4 v[90:91], v[124:127], off
	global_store_dwordx4 v[90:91], v[120:123], off offset:16
	ds_read_b32 v80, v130 offset:8320
	v_lshl_add_u64 v[82:83], v[88:89], 1, s[6:7]
	s_waitcnt lgkmcnt(0)
	v_pk_mul_f32 v[88:89], v[124:125], v[80:81] op_sel_hi:[1,0]
	v_pk_mul_f32 v[96:97], v[126:127], v[80:81] op_sel_hi:[1,0]
	v_pk_mul_f32 v[98:99], v[120:121], v[80:81] op_sel_hi:[1,0]
	v_pk_mul_f32 v[100:101], v[122:123], v[80:81] op_sel_hi:[1,0]
	v_pk_mul_f32 v[74:75], v[96:97], v[148:149]
	v_pk_mul_f32 v[72:73], v[88:89], v[146:147]
	v_pk_mul_f32 v[78:79], v[100:101], v[152:153]
	v_pk_mul_f32 v[76:77], v[98:99], v[150:151]
	v_cvt_pk_bf16_f32 v72, v72, v73
	v_cvt_pk_bf16_f32 v73, v74, v75
	v_cvt_pk_bf16_f32 v74, v76, v77
	v_cvt_pk_bf16_f32 v75, v78, v79
	global_store_dwordx4 v[82:83], v[72:75], off
	global_store_dwordx4 v[90:91], v[112:115], off offset:512
	global_store_dwordx4 v[90:91], v[104:107], off offset:528
	s_nop 0
	v_add_u32_e32 v88, 48, v214
	v_ashrrev_i32_e32 v89, 31, v88
	v_pk_mul_f32 v[96:97], v[112:113], v[80:81] op_sel_hi:[1,0]
	v_pk_mul_f32 v[98:99], v[114:115], v[80:81] op_sel_hi:[1,0]
	v_pk_mul_f32 v[100:101], v[104:105], v[80:81] op_sel_hi:[1,0]
	v_pk_mul_f32 v[80:81], v[106:107], v[80:81] op_sel_hi:[1,0]
	v_lshlrev_b64 v[88:89], 10, v[88:89]
	v_lshl_add_u64 v[88:89], v[88:89], 0, v[212:213]
	v_lshl_add_u64 v[90:91], v[88:89], 2, s[12:13]
	v_pk_mul_f32 v[74:75], v[98:99], v[156:157]
	v_pk_mul_f32 v[72:73], v[96:97], v[154:155]
	v_pk_mul_f32 v[78:79], v[80:81], v[160:161]
	v_pk_mul_f32 v[76:77], v[100:101], v[158:159]
	v_cvt_pk_bf16_f32 v72, v72, v73
	v_cvt_pk_bf16_f32 v73, v74, v75
	v_cvt_pk_bf16_f32 v74, v76, v77
	v_cvt_pk_bf16_f32 v75, v78, v79
	global_store_dwordx4 v[82:83], v[72:75], off offset:256
	global_store_dwordx4 v[90:91], v[92:95], off
	global_store_dwordx4 v[90:91], v[84:87], off offset:16
	ds_read_b32 v80, v130 offset:8384
	v_lshl_add_u64 v[82:83], v[88:89], 1, s[6:7]
	s_waitcnt lgkmcnt(0)
;     __device__ __forceinline__ void fused(pg8::f32x4 (&acc)[2][2][4][2], const pg8::Unit& u, int wr, int wc, int fr, int fq, LAS unsigned char* lds, int wid, int lane) const {
;     ...
;         for (int ai = 0; ai < 2; ++ai)
; #pragma unroll
;             for (int m = 0; m < 4; ++m) { const int r = ai * 128 + wr * 64 + m * 16 + fr; const float s2 = S[r]; const size_t off = (size_t)(b * TB + u.pm * 256 + r) * D + col0;
; #pragma unroll
;                 for (int bj = 0; bj < 2; ++bj) { const f32x4 x0 = acc[ai][bj][m][0], x1 = acc[ai][bj][m][1];
;                     *(f32x4*)(xout + off + bj * 128) = x0; *(f32x4*)(xout + off + bj * 128 + 4) = x1;
;                     const f32x4 h0 = *(const f32x4*)(g2 + col0 + bj * 128), h1 = *(const f32x4*)(g2 + col0 + bj * 128 + 4);
;                     st8bf(H2o + off + bj * 128, x0 * s2 * h0, x1 * s2 * h1); }
;                 asm volatile("" ::: "memory"); }
	v_pk_mul_f32 v[88:89], v[92:93], v[80:81] op_sel_hi:[1,0]
	v_pk_mul_f32 v[92:93], v[94:95], v[80:81] op_sel_hi:[1,0]
	v_pk_mul_f32 v[84:85], v[84:85], v[80:81] op_sel_hi:[1,0]
	v_pk_mul_f32 v[86:87], v[86:87], v[80:81] op_sel_hi:[1,0]
	v_pk_mul_f32 v[74:75], v[92:93], v[148:149]
	v_pk_mul_f32 v[72:73], v[88:89], v[146:147]
	v_pk_mul_f32 v[78:79], v[86:87], v[152:153]
	v_pk_mul_f32 v[76:77], v[84:85], v[150:151]
	v_cvt_pk_bf16_f32 v72, v72, v73
	v_cvt_pk_bf16_f32 v73, v74, v75
	v_cvt_pk_bf16_f32 v74, v76, v77
	v_cvt_pk_bf16_f32 v75, v78, v79
	global_store_dwordx4 v[82:83], v[72:75], off
	global_store_dwordx4 v[90:91], v[68:71], off offset:512
	global_store_dwordx4 v[90:91], v[64:67], off offset:528
	s_nop 0
	v_add_u32_e32 v84, 0x80, v214
	v_ashrrev_i32_e32 v85, 31, v84
	v_pk_mul_f32 v[68:69], v[68:69], v[80:81] op_sel_hi:[1,0]
	v_pk_mul_f32 v[70:71], v[70:71], v[80:81] op_sel_hi:[1,0]
	v_pk_mul_f32 v[64:65], v[64:65], v[80:81] op_sel_hi:[1,0]
	v_pk_mul_f32 v[66:67], v[66:67], v[80:81] op_sel_hi:[1,0]
	v_lshlrev_b64 v[84:85], 10, v[84:85]
	v_lshl_add_u64 v[84:85], v[84:85], 0, v[212:213]
	v_lshl_add_u64 v[86:87], v[84:85], 2, s[12:13]
	v_pk_mul_f32 v[70:71], v[70:71], v[156:157]
	v_pk_mul_f32 v[68:69], v[68:69], v[154:155]
	v_pk_mul_f32 v[72:73], v[66:67], v[160:161]
	v_pk_mul_f32 v[66:67], v[64:65], v[158:159]
	v_cvt_pk_bf16_f32 v64, v68, v69
	v_cvt_pk_bf16_f32 v65, v70, v71
	v_cvt_pk_bf16_f32 v66, v66, v67
	v_cvt_pk_bf16_f32 v67, v72, v73
	global_store_dwordx4 v[82:83], v[64:67], off offset:256
	global_store_dwordx4 v[86:87], v[60:63], off
	global_store_dwordx4 v[86:87], v[56:59], off offset:16
	ds_read_b32 v72, v130 offset:8704
	v_lshl_add_u64 v[74:75], v[84:85], 1, s[6:7]
	s_waitcnt lgkmcnt(0)
	v_pk_mul_f32 v[60:61], v[60:61], v[72:73] op_sel_hi:[1,0]
	v_pk_mul_f32 v[62:63], v[62:63], v[72:73] op_sel_hi:[1,0]
	v_pk_mul_f32 v[56:57], v[56:57], v[72:73] op_sel_hi:[1,0]
	v_pk_mul_f32 v[58:59], v[58:59], v[72:73] op_sel_hi:[1,0]
	v_pk_mul_f32 v[62:63], v[62:63], v[148:149]
	v_pk_mul_f32 v[60:61], v[60:61], v[146:147]
	v_pk_mul_f32 v[64:65], v[58:59], v[152:153]
	v_pk_mul_f32 v[58:59], v[56:57], v[150:151]
	v_cvt_pk_bf16_f32 v56, v60, v61
	v_cvt_pk_bf16_f32 v57, v62, v63
	v_cvt_pk_bf16_f32 v58, v58, v59
	v_cvt_pk_bf16_f32 v59, v64, v65
	global_store_dwordx4 v[74:75], v[56:59], off
	global_store_dwordx4 v[86:87], v[52:55], off offset:512
	global_store_dwordx4 v[86:87], v[48:51], off offset:528
	s_nop 0
	v_add_u32_e32 v64, 0x90, v214
	v_ashrrev_i32_e32 v65, 31, v64
	v_pk_mul_f32 v[52:53], v[52:53], v[72:73] op_sel_hi:[1,0]
	v_pk_mul_f32 v[54:55], v[54:55], v[72:73] op_sel_hi:[1,0]
	v_pk_mul_f32 v[48:49], v[48:49], v[72:73] op_sel_hi:[1,0]
	v_pk_mul_f32 v[50:51], v[50:51], v[72:73] op_sel_hi:[1,0]
	v_lshlrev_b64 v[64:65], 10, v[64:65]
	v_lshl_add_u64 v[64:65], v[64:65], 0, v[212:213]
	v_lshl_add_u64 v[66:67], v[64:65], 2, s[12:13]
	v_pk_mul_f32 v[54:55], v[54:55], v[156:157]
	v_pk_mul_f32 v[52:53], v[52:53], v[154:155]
	v_pk_mul_f32 v[56:57], v[50:51], v[160:161]
	v_pk_mul_f32 v[50:51], v[48:49], v[158:159]
	v_cvt_pk_bf16_f32 v48, v52, v53
	v_cvt_pk_bf16_f32 v49, v54, v55
	v_cvt_pk_bf16_f32 v50, v50, v51
	v_cvt_pk_bf16_f32 v51, v56, v57
	global_store_dwordx4 v[74:75], v[48:51], off offset:256
	global_store_dwordx4 v[66:67], v[44:47], off
	global_store_dwordx4 v[66:67], v[40:43], off offset:16
	ds_read_b32 v56, v130 offset:8768
	v_lshl_add_u64 v[58:59], v[64:65], 1, s[6:7]
	s_waitcnt lgkmcnt(0)
;     __device__ __forceinline__ void fused(pg8::f32x4 (&acc)[2][2][4][2], const pg8::Unit& u, int wr, int wc, int fr, int fq, LAS unsigned char* lds, int wid, int lane) const {
;     ...
;         for (int ai = 0; ai < 2; ++ai)
; #pragma unroll
;             for (int m = 0; m < 4; ++m) { const int r = ai * 128 + wr * 64 + m * 16 + fr; const float s2 = S[r]; const size_t off = (size_t)(b * TB + u.pm * 256 + r) * D + col0;
; #pragma unroll
;                 for (int bj = 0; bj < 2; ++bj) { const f32x4 x0 = acc[ai][bj][m][0], x1 = acc[ai][bj][m][1];
;                     *(f32x4*)(xout + off + bj * 128) = x0; *(f32x4*)(xout + off + bj * 128 + 4) = x1;
;                     const f32x4 h0 = *(const f32x4*)(g2 + col0 + bj * 128), h1 = *(const f32x4*)(g2 + col0 + bj * 128 + 4);
;                     st8bf(H2o + off + bj * 128, x0 * s2 * h0, x1 * s2 * h1); }
;                 asm volatile("" ::: "memory"); }
	v_pk_mul_f32 v[44:45], v[44:45], v[56:57] op_sel_hi:[1,0]
	v_pk_mul_f32 v[46:47], v[46:47], v[56:57] op_sel_hi:[1,0]
	v_pk_mul_f32 v[40:41], v[40:41], v[56:57] op_sel_hi:[1,0]
	v_pk_mul_f32 v[42:43], v[42:43], v[56:57] op_sel_hi:[1,0]
	v_pk_mul_f32 v[46:47], v[46:47], v[148:149]
	v_pk_mul_f32 v[44:45], v[44:45], v[146:147]
	v_pk_mul_f32 v[48:49], v[42:43], v[152:153]
	v_pk_mul_f32 v[42:43], v[40:41], v[150:151]
	v_cvt_pk_bf16_f32 v40, v44, v45
	v_cvt_pk_bf16_f32 v41, v46, v47
	v_cvt_pk_bf16_f32 v42, v42, v43
	v_cvt_pk_bf16_f32 v43, v48, v49
	global_store_dwordx4 v[58:59], v[40:43], off
	global_store_dwordx4 v[66:67], v[36:39], off offset:512
	global_store_dwordx4 v[66:67], v[32:35], off offset:528
	s_nop 0
	v_add_u32_e32 v48, 0xa0, v214
	v_ashrrev_i32_e32 v49, 31, v48
	v_pk_mul_f32 v[36:37], v[36:37], v[56:57] op_sel_hi:[1,0]
	v_pk_mul_f32 v[38:39], v[38:39], v[56:57] op_sel_hi:[1,0]
	v_pk_mul_f32 v[32:33], v[32:33], v[56:57] op_sel_hi:[1,0]
	v_pk_mul_f32 v[34:35], v[34:35], v[56:57] op_sel_hi:[1,0]
	v_lshlrev_b64 v[48:49], 10, v[48:49]
	v_lshl_add_u64 v[48:49], v[48:49], 0, v[212:213]
	v_lshl_add_u64 v[50:51], v[48:49], 2, s[12:13]
	v_pk_mul_f32 v[38:39], v[38:39], v[156:157]
	v_pk_mul_f32 v[36:37], v[36:37], v[154:155]
	v_pk_mul_f32 v[40:41], v[34:35], v[160:161]
	v_pk_mul_f32 v[34:35], v[32:33], v[158:159]
	v_cvt_pk_bf16_f32 v32, v36, v37
	v_cvt_pk_bf16_f32 v33, v38, v39
	v_cvt_pk_bf16_f32 v34, v34, v35
	v_cvt_pk_bf16_f32 v35, v40, v41
	global_store_dwordx4 v[58:59], v[32:35], off offset:256
	global_store_dwordx4 v[50:51], v[28:31], off
	global_store_dwordx4 v[50:51], v[24:27], off offset:16
	ds_read_b32 v40, v130 offset:8832
	v_lshl_add_u64 v[42:43], v[48:49], 1, s[6:7]
	s_waitcnt lgkmcnt(0)
	v_pk_mul_f32 v[28:29], v[28:29], v[40:41] op_sel_hi:[1,0]
	v_pk_mul_f32 v[30:31], v[30:31], v[40:41] op_sel_hi:[1,0]
	v_pk_mul_f32 v[24:25], v[24:25], v[40:41] op_sel_hi:[1,0]
	v_pk_mul_f32 v[26:27], v[26:27], v[40:41] op_sel_hi:[1,0]
	v_pk_mul_f32 v[30:31], v[30:31], v[148:149]
	v_pk_mul_f32 v[28:29], v[28:29], v[146:147]
	v_pk_mul_f32 v[32:33], v[26:27], v[152:153]
	v_pk_mul_f32 v[26:27], v[24:25], v[150:151]
	v_cvt_pk_bf16_f32 v24, v28, v29
	v_cvt_pk_bf16_f32 v25, v30, v31
	v_cvt_pk_bf16_f32 v26, v26, v27
	v_cvt_pk_bf16_f32 v27, v32, v33
	global_store_dwordx4 v[42:43], v[24:27], off
	global_store_dwordx4 v[50:51], v[20:23], off offset:512
	global_store_dwordx4 v[50:51], v[16:19], off offset:528
	s_nop 0
	v_add_u32_e32 v32, 0xb0, v214
	v_ashrrev_i32_e32 v33, 31, v32
	v_pk_mul_f32 v[20:21], v[20:21], v[40:41] op_sel_hi:[1,0]
	v_pk_mul_f32 v[22:23], v[22:23], v[40:41] op_sel_hi:[1,0]
	v_pk_mul_f32 v[16:17], v[16:17], v[40:41] op_sel_hi:[1,0]
	v_pk_mul_f32 v[18:19], v[18:19], v[40:41] op_sel_hi:[1,0]
	v_lshlrev_b64 v[32:33], 10, v[32:33]
	v_lshl_add_u64 v[32:33], v[32:33], 0, v[212:213]
	v_lshl_add_u64 v[34:35], v[32:33], 2, s[12:13]
	v_pk_mul_f32 v[22:23], v[22:23], v[156:157]
	v_pk_mul_f32 v[20:21], v[20:21], v[154:155]
	v_pk_mul_f32 v[24:25], v[18:19], v[160:161]
	v_pk_mul_f32 v[18:19], v[16:17], v[158:159]
	v_cvt_pk_bf16_f32 v16, v20, v21
	v_cvt_pk_bf16_f32 v17, v22, v23
	v_cvt_pk_bf16_f32 v18, v18, v19
	v_cvt_pk_bf16_f32 v19, v24, v25
	global_store_dwordx4 v[42:43], v[16:19], off offset:256
	global_store_dwordx4 v[34:35], v[12:15], off
	global_store_dwordx4 v[34:35], v[8:11], off offset:16
	ds_read_b32 v24, v130 offset:8896
	v_lshl_add_u64 v[26:27], v[32:33], 1, s[6:7]
	s_waitcnt lgkmcnt(0)
	v_pk_mul_f32 v[12:13], v[12:13], v[24:25] op_sel_hi:[1,0]
	v_pk_mul_f32 v[14:15], v[14:15], v[24:25] op_sel_hi:[1,0]
	v_pk_mul_f32 v[8:9], v[8:9], v[24:25] op_sel_hi:[1,0]
	v_pk_mul_f32 v[10:11], v[10:11], v[24:25] op_sel_hi:[1,0]
	v_pk_mul_f32 v[14:15], v[14:15], v[148:149]
	v_pk_mul_f32 v[12:13], v[12:13], v[146:147]
	v_pk_mul_f32 v[16:17], v[10:11], v[152:153]
	v_pk_mul_f32 v[10:11], v[8:9], v[150:151]
	v_cvt_pk_bf16_f32 v8, v12, v13
	v_cvt_pk_bf16_f32 v9, v14, v15
	v_cvt_pk_bf16_f32 v10, v10, v11
	v_cvt_pk_bf16_f32 v11, v16, v17
	global_store_dwordx4 v[26:27], v[8:11], off
	global_store_dwordx4 v[34:35], v[4:7], off offset:512
	global_store_dwordx4 v[34:35], v[0:3], off offset:528
	s_nop 0
	v_pk_mul_f32 v[4:5], v[4:5], v[24:25] op_sel_hi:[1,0]
	v_pk_mul_f32 v[6:7], v[6:7], v[24:25] op_sel_hi:[1,0]
	v_pk_mul_f32 v[0:1], v[0:1], v[24:25] op_sel_hi:[1,0]
	v_pk_mul_f32 v[2:3], v[2:3], v[24:25] op_sel_hi:[1,0]
	v_pk_mul_f32 v[6:7], v[6:7], v[156:157]
	v_pk_mul_f32 v[4:5], v[4:5], v[154:155]
	v_pk_mul_f32 v[8:9], v[2:3], v[160:161]
	v_pk_mul_f32 v[2:3], v[0:1], v[158:159]
	v_cvt_pk_bf16_f32 v0, v4, v5
	v_cvt_pk_bf16_f32 v1, v6, v7
	v_cvt_pk_bf16_f32 v2, v2, v3
	v_cvt_pk_bf16_f32 v3, v8, v9
	global_store_dwordx4 v[26:27], v[0:3], off offset:256
